# m12 + per-tile GEMM accumulator zero-init with 64 v_mov_b64 (inline 0) instead of 128 v_mov_b32 (fp8 GEMMs)
# baseline (speedup 1.0000x reference)
; template <class Epi, class Sched, bool F8 = false>
; __device__ __forceinline__ void gemm_phase(LAS unsigned char* lds, const Gemm g, const Sched& S, const Epi& E) {
;     ...
;         const bool has_next = S.next(ui + 1, nxt);
;         const char* nA = has_next ? (const char*)g.A + (size_t)nxt.pm * tstep : cA; const char* nB = has_next ? (const char*)g.Bt + (size_t)nxt.pn * tstep : cB;
; #pragma unroll 1
;         for (int t = 0; t < nt; t += 2) {
;             const bool last = (t == nt - 2);
;             if constexpr (Epi::PREF) { if (last) E.prefetch(pfv, cur, wr, fr); }
;             const char* a1 = cA + (size_t)(t + 1) * kstep;
;             const char* a2 = last ? nA : cA + (size_t)(t + 2) * kstep; const char* b2 = last ? nB : cB + (size_t)(t + 2) * kstep;
;             const char* a3 = a2 + kstep; const char* b3 = b2 + kstep;
;     ...
; #pragma unroll
;         for (int a = 0; a < 2; ++a)
; #pragma unroll
;             for (int b = 0; b < 2; ++b)
; #pragma unroll
;                 for (int m = 0; m < 4; ++m)
; #pragma unroll
;                     for (int n = 0; n < 2; ++n) acc[a][b][m][n] = (f32x4){0.f, 0.f, 0.f, 0.f};
;         cur = nxt; cA = nA; cB = nB; ++ui;
.LBB0_240:
	s_ashr_i32 s25, s24, 31
	s_lshl_b64 s[26:27], s[24:25], 18
	s_add_u32 s26, s66, s26
	s_addc_u32 s27, s67, s27
	s_and_b64 s[84:85], s[10:11], exec
	s_cselect_b32 s25, s27, s13
	s_cselect_b32 s43, s26, s12
	s_ashr_i32 s23, s22, 31
	s_lshl_b64 s[84:85], s[22:23], 18
	s_add_u32 s84, s5, s84
	s_addc_u32 s85, s62, s85
	s_and_b64 vcc, s[10:11], exec
	s_cselect_b32 s23, s85, s37
	s_cselect_b32 s45, s84, s36
	s_add_u32 s12, s12, 0x20080
	v_lshl_add_u32 v190, s56, 8, v218
	s_addc_u32 s13, s13, 0
	v_ashrrev_i32_e32 v191, 31, v190
	s_add_u32 s79, s36, 0x100
	v_mov_b64_e32 v[32:33], 0
	v_lshl_add_u64 v[192:193], v[190:191], 3, s[18:19]
	s_addc_u32 s81, s37, 0
	s_mov_b32 s97, -2
	v_mov_b64_e32 v[34:35], 0
	v_mov_b64_e32 v[36:37], 0
	v_mov_b64_e32 v[38:39], 0
	v_mov_b64_e32 v[40:41], 0
	v_mov_b64_e32 v[42:43], 0
	v_mov_b64_e32 v[44:45], 0
	v_mov_b64_e32 v[46:47], 0
	v_mov_b64_e32 v[48:49], 0
	v_mov_b64_e32 v[50:51], 0
	v_mov_b64_e32 v[52:53], 0
	v_mov_b64_e32 v[54:55], 0
	v_mov_b64_e32 v[56:57], 0
	v_mov_b64_e32 v[58:59], 0
	v_mov_b64_e32 v[60:61], 0
	v_mov_b64_e32 v[62:63], 0
	v_mov_b64_e32 v[64:65], 0
	v_mov_b64_e32 v[66:67], 0
	v_mov_b64_e32 v[68:69], 0
	v_mov_b64_e32 v[70:71], 0
	v_mov_b64_e32 v[72:73], 0
	v_mov_b64_e32 v[74:75], 0
	v_mov_b64_e32 v[76:77], 0
	v_mov_b64_e32 v[78:79], 0
	v_mov_b64_e32 v[80:81], 0
	v_mov_b64_e32 v[82:83], 0
	v_mov_b64_e32 v[84:85], 0
	v_mov_b64_e32 v[86:87], 0
	v_mov_b64_e32 v[88:89], 0
	v_mov_b64_e32 v[90:91], 0
	v_mov_b64_e32 v[92:93], 0
	v_mov_b64_e32 v[94:95], 0
	v_mov_b64_e32 v[96:97], 0
	v_mov_b64_e32 v[98:99], 0
	v_mov_b64_e32 v[100:101], 0
	v_mov_b64_e32 v[102:103], 0
	v_mov_b64_e32 v[104:105], 0
	v_mov_b64_e32 v[106:107], 0
	v_mov_b64_e32 v[108:109], 0
	v_mov_b64_e32 v[110:111], 0
	v_mov_b64_e32 v[112:113], 0
	v_mov_b64_e32 v[114:115], 0
	v_mov_b64_e32 v[116:117], 0
	v_mov_b64_e32 v[118:119], 0
	v_mov_b64_e32 v[120:121], 0
	v_mov_b64_e32 v[122:123], 0
	v_mov_b64_e32 v[124:125], 0
	v_mov_b64_e32 v[126:127], 0
	v_mov_b64_e32 v[128:129], 0
	v_mov_b64_e32 v[130:131], 0
	v_mov_b64_e32 v[132:133], 0
	v_mov_b64_e32 v[134:135], 0
	v_mov_b64_e32 v[136:137], 0
	v_mov_b64_e32 v[138:139], 0
	v_mov_b64_e32 v[140:141], 0
	v_mov_b64_e32 v[142:143], 0
	v_mov_b64_e32 v[144:145], 0
	v_mov_b64_e32 v[146:147], 0
	v_mov_b64_e32 v[148:149], 0
	v_mov_b64_e32 v[150:151], 0
	v_mov_b64_e32 v[152:153], 0
	v_mov_b64_e32 v[154:155], 0
	v_mov_b64_e32 v[156:157], 0
	v_mov_b64_e32 v[158:159], 0
	s_branch .LBB0_242

; template <class Epi, class Sched, bool F8 = false>
; __device__ __forceinline__ void gemm_phase(LAS unsigned char* lds, const Gemm g, const Sched& S, const Epi& E) {
;     ...
;             const char* a1 = cA + (size_t)(t + 1) * kstep;
;             const char* a2 = last ? nA : cA + (size_t)(t + 2) * kstep; const char* b2 = last ? nB : cB + (size_t)(t + 2) * kstep;
;             const char* a3 = a2 + kstep; const char* b3 = b2 + kstep;
;     ...
; #pragma unroll
;         for (int a = 0; a < 2; ++a)
; #pragma unroll
;             for (int b = 0; b < 2; ++b)
; #pragma unroll
;                 for (int m = 0; m < 4; ++m)
; #pragma unroll
;                     for (int n = 0; n < 2; ++n) acc[a][b][m][n] = (f32x4){0.f, 0.f, 0.f, 0.f};
;         cur = nxt; cA = nA; cB = nB; ++ui;
.LBB0_312:
	s_add_u32 s14, s84, 0x58080
	s_addc_u32 s15, s85, 0
	s_add_u32 s45, s36, 0x100
	v_mov_b64_e32 v[32:33], 0
	s_addc_u32 s56, s37, 0
	s_mov_b32 s81, -2
	v_mov_b64_e32 v[34:35], 0
	v_mov_b64_e32 v[36:37], 0
	v_mov_b64_e32 v[38:39], 0
	v_mov_b64_e32 v[40:41], 0
	v_mov_b64_e32 v[42:43], 0
	v_mov_b64_e32 v[44:45], 0
	v_mov_b64_e32 v[46:47], 0
	v_mov_b64_e32 v[48:49], 0
	v_mov_b64_e32 v[50:51], 0
	v_mov_b64_e32 v[52:53], 0
	v_mov_b64_e32 v[54:55], 0
	v_mov_b64_e32 v[56:57], 0
	v_mov_b64_e32 v[58:59], 0
	v_mov_b64_e32 v[60:61], 0
	v_mov_b64_e32 v[62:63], 0
	v_mov_b64_e32 v[64:65], 0
	v_mov_b64_e32 v[66:67], 0
	v_mov_b64_e32 v[68:69], 0
	v_mov_b64_e32 v[70:71], 0
	v_mov_b64_e32 v[72:73], 0
	v_mov_b64_e32 v[74:75], 0
	v_mov_b64_e32 v[76:77], 0
	v_mov_b64_e32 v[78:79], 0
	v_mov_b64_e32 v[80:81], 0
	v_mov_b64_e32 v[82:83], 0
	v_mov_b64_e32 v[84:85], 0
	v_mov_b64_e32 v[86:87], 0
	v_mov_b64_e32 v[88:89], 0
	v_mov_b64_e32 v[90:91], 0
	v_mov_b64_e32 v[92:93], 0
	v_mov_b64_e32 v[94:95], 0
	v_mov_b64_e32 v[96:97], 0
	v_mov_b64_e32 v[98:99], 0
	v_mov_b64_e32 v[100:101], 0
	v_mov_b64_e32 v[102:103], 0
	v_mov_b64_e32 v[104:105], 0
	v_mov_b64_e32 v[106:107], 0
	v_mov_b64_e32 v[108:109], 0
	v_mov_b64_e32 v[110:111], 0
	v_mov_b64_e32 v[112:113], 0
	v_mov_b64_e32 v[114:115], 0
	v_mov_b64_e32 v[116:117], 0
	v_mov_b64_e32 v[118:119], 0
	v_mov_b64_e32 v[120:121], 0
	v_mov_b64_e32 v[122:123], 0
	v_mov_b64_e32 v[124:125], 0
	v_mov_b64_e32 v[126:127], 0
	v_mov_b64_e32 v[128:129], 0
	v_mov_b64_e32 v[130:131], 0
	v_mov_b64_e32 v[132:133], 0
	v_mov_b64_e32 v[134:135], 0
	v_mov_b64_e32 v[136:137], 0
	v_mov_b64_e32 v[138:139], 0
	v_mov_b64_e32 v[140:141], 0
	v_mov_b64_e32 v[142:143], 0
	v_mov_b64_e32 v[144:145], 0
	v_mov_b64_e32 v[146:147], 0
	v_mov_b64_e32 v[148:149], 0
	v_mov_b64_e32 v[150:151], 0
	v_mov_b64_e32 v[152:153], 0
	v_mov_b64_e32 v[154:155], 0
	v_mov_b64_e32 v[156:157], 0
	v_mov_b64_e32 v[158:159], 0

; template <class Epi, class Sched, bool F8 = false>
; __device__ __forceinline__ void gemm_phase(LAS unsigned char* lds, const Gemm g, const Sched& S, const Epi& E) {
;     ...
;         const bool has_next = S.next(ui + 1, nxt);
;         const char* nA = has_next ? (const char*)g.A + (size_t)nxt.pm * tstep : cA; const char* nB = has_next ? (const char*)g.Bt + (size_t)nxt.pn * tstep : cB;
; #pragma unroll 1
;         for (int t = 0; t < nt; t += 2) {
;             const bool last = (t == nt - 2);
;             if constexpr (Epi::PREF) { if (last) E.prefetch(pfv, cur, wr, fr); }
;             const char* a1 = cA + (size_t)(t + 1) * kstep;
;             const char* a2 = last ? nA : cA + (size_t)(t + 2) * kstep; const char* b2 = last ? nB : cB + (size_t)(t + 2) * kstep;
;             const char* a3 = a2 + kstep; const char* b3 = b2 + kstep;
;     ...
; #pragma unroll
;         for (int a = 0; a < 2; ++a)
; #pragma unroll
;             for (int b = 0; b < 2; ++b)
; #pragma unroll
;                 for (int m = 0; m < 4; ++m)
; #pragma unroll
;                     for (int n = 0; n < 2; ++n) acc[a][b][m][n] = (f32x4){0.f, 0.f, 0.f, 0.f};
;         cur = nxt; cA = nA; cB = nB; ++ui;
.LBB0_451:
	s_ashr_i32 s19, s18, 31
	s_lshl_b64 s[20:21], s[18:19], 18
	v_readlane_b32 s17, v255, 24
	s_add_u32 s20, s17, s20
	v_readlane_b32 s17, v255, 25
	s_addc_u32 s21, s17, s21
	s_and_b64 s[22:23], s[10:11], exec
	s_cselect_b32 s19, s21, s25
	s_cselect_b32 s45, s20, s24
	s_ashr_i32 s17, s16, 31
	s_lshl_b64 s[22:23], s[16:17], 18
	s_add_u32 s22, s66, s22
	s_addc_u32 s23, s67, s23
	s_and_b64 s[36:37], s[10:11], exec
	s_cselect_b32 s17, s23, s27
	s_cselect_b32 s56, s22, s26
	s_add_u32 s24, s24, 0x20080
	s_addc_u32 s25, s25, 0
	s_add_u32 s76, s26, 0x100
	v_mov_b64_e32 v[32:33], 0
	s_addc_u32 s77, s27, 0
	s_mov_b32 s78, -2
	v_mov_b64_e32 v[34:35], 0
	v_mov_b64_e32 v[36:37], 0
	v_mov_b64_e32 v[38:39], 0
	v_mov_b64_e32 v[40:41], 0
	v_mov_b64_e32 v[42:43], 0
	v_mov_b64_e32 v[44:45], 0
	v_mov_b64_e32 v[46:47], 0
	v_mov_b64_e32 v[48:49], 0
	v_mov_b64_e32 v[50:51], 0
	v_mov_b64_e32 v[52:53], 0
	v_mov_b64_e32 v[54:55], 0
	v_mov_b64_e32 v[56:57], 0
	v_mov_b64_e32 v[58:59], 0
	v_mov_b64_e32 v[60:61], 0
	v_mov_b64_e32 v[62:63], 0
	v_mov_b64_e32 v[64:65], 0
	v_mov_b64_e32 v[66:67], 0
	v_mov_b64_e32 v[68:69], 0
	v_mov_b64_e32 v[70:71], 0
	v_mov_b64_e32 v[72:73], 0
	v_mov_b64_e32 v[74:75], 0
	v_mov_b64_e32 v[76:77], 0
	v_mov_b64_e32 v[78:79], 0
	v_mov_b64_e32 v[80:81], 0
	v_mov_b64_e32 v[82:83], 0
	v_mov_b64_e32 v[84:85], 0
	v_mov_b64_e32 v[86:87], 0
	v_mov_b64_e32 v[88:89], 0
	v_mov_b64_e32 v[90:91], 0
	v_mov_b64_e32 v[92:93], 0
	v_mov_b64_e32 v[94:95], 0
	v_mov_b64_e32 v[96:97], 0
	v_mov_b64_e32 v[98:99], 0
	v_mov_b64_e32 v[100:101], 0
	v_mov_b64_e32 v[102:103], 0
	v_mov_b64_e32 v[104:105], 0
	v_mov_b64_e32 v[106:107], 0
	v_mov_b64_e32 v[108:109], 0
	v_mov_b64_e32 v[110:111], 0
	v_mov_b64_e32 v[112:113], 0
	v_mov_b64_e32 v[114:115], 0
	v_mov_b64_e32 v[116:117], 0
	v_mov_b64_e32 v[118:119], 0
	v_mov_b64_e32 v[120:121], 0
	v_mov_b64_e32 v[122:123], 0
	v_mov_b64_e32 v[124:125], 0
	v_mov_b64_e32 v[126:127], 0
	v_mov_b64_e32 v[128:129], 0
	v_mov_b64_e32 v[130:131], 0
	v_mov_b64_e32 v[132:133], 0
	v_mov_b64_e32 v[134:135], 0
	v_mov_b64_e32 v[136:137], 0
	v_mov_b64_e32 v[138:139], 0
	v_mov_b64_e32 v[140:141], 0
	v_mov_b64_e32 v[142:143], 0
	v_mov_b64_e32 v[144:145], 0
	v_mov_b64_e32 v[146:147], 0
	v_mov_b64_e32 v[148:149], 0
	v_mov_b64_e32 v[150:151], 0
	v_mov_b64_e32 v[152:153], 0
	v_mov_b64_e32 v[154:155], 0
	v_mov_b64_e32 v[156:157], 0
	v_mov_b64_e32 v[158:159], 0
